# baseline (speedup 1.0000x reference)
; #define LAS __attribute__((address_space(3)))
; __device__ __forceinline__ int crow(int reg, int h) { return (reg & 3) + 8 * (reg >> 2) + 4 * h; }
; #define WAVE_FENCE() asm volatile("s_waitcnt lgkmcnt(0)" ::: "memory")
; template <bool OUT>
; __device__ __forceinline__ void ssm_fast(KArgs ap, int l, LAS unsigned char* lds, const Ctx cx) {
;     ...
;                 for (int i = 0; i < 16; ++i) *(LAS float*)(BU + (crow(i, hh) * 128 + nb * 32 + r) * 4) = c[i]; }
;             WAVE_FENCE();
; #pragma unroll 4
;             for (int t = 0; t < 32; ++t) {
;                 const float br = *(const LAS float*)(BU + (t * 128 + p) * 4), bi = *(const LAS float*)(BU + (t * 128 + 64 + p) * 4);
;                 const float nr = are * sr - aim * si + br, ni = are * si + aim * sr + bi; sr = nr; si = ni;
.LBB0_171:
	v_permlane32_swap_b32_e32 v0, v16
	v_permlane32_swap_b32_e32 v1, v17
	v_permlane32_swap_b32_e32 v2, v18
	v_permlane32_swap_b32_e32 v3, v19
	v_permlane32_swap_b32_e32 v4, v20
	v_permlane32_swap_b32_e32 v5, v21
	v_permlane32_swap_b32_e32 v6, v22
	v_permlane32_swap_b32_e32 v7, v23
	v_permlane32_swap_b32_e32 v8, v24
	v_permlane32_swap_b32_e32 v9, v25
	v_permlane32_swap_b32_e32 v10, v26
	v_permlane32_swap_b32_e32 v11, v27
	v_permlane32_swap_b32_e32 v12, v28
	v_permlane32_swap_b32_e32 v13, v29
	v_permlane32_swap_b32_e32 v14, v30
	v_permlane32_swap_b32_e32 v15, v31
	v_permlane32_swap_b32_e32 v32, v48
	v_permlane32_swap_b32_e32 v33, v49
	v_permlane32_swap_b32_e32 v34, v50
	v_permlane32_swap_b32_e32 v35, v51
	v_permlane32_swap_b32_e32 v36, v52
	v_permlane32_swap_b32_e32 v37, v53
	v_permlane32_swap_b32_e32 v38, v54
	v_permlane32_swap_b32_e32 v39, v55
	v_permlane32_swap_b32_e32 v40, v56
	v_permlane32_swap_b32_e32 v41, v57
	v_permlane32_swap_b32_e32 v42, v58
	v_permlane32_swap_b32_e32 v43, v59
	v_permlane32_swap_b32_e32 v44, v60
	v_permlane32_swap_b32_e32 v45, v61
	v_permlane32_swap_b32_e32 v46, v62
	v_permlane32_swap_b32_e32 v47, v63
	v_pk_mul_f32 v[114:115], v[80:81], v[92:93] op_sel:[1,1] op_sel_hi:[0,1]
	v_pk_fma_f32 v[114:115], v[80:81], v[92:93], v[114:115] op_sel_hi:[1,0,1] neg_lo:[0,0,1]
	v_add_f32_e32 v92, v114, v0
	v_add_f32_e32 v93, v115, v32
	v_pk_mul_f32 v[114:115], v[80:81], v[92:93] op_sel:[1,1] op_sel_hi:[0,1]
	v_pk_fma_f32 v[114:115], v[80:81], v[92:93], v[114:115] op_sel_hi:[1,0,1] neg_lo:[0,0,1]
	v_add_f32_e32 v92, v114, v1
	v_add_f32_e32 v93, v115, v33
	v_pk_mul_f32 v[114:115], v[80:81], v[92:93] op_sel:[1,1] op_sel_hi:[0,1]
	v_pk_fma_f32 v[114:115], v[80:81], v[92:93], v[114:115] op_sel_hi:[1,0,1] neg_lo:[0,0,1]
	v_add_f32_e32 v92, v114, v2
	v_add_f32_e32 v93, v115, v34
	v_pk_mul_f32 v[114:115], v[80:81], v[92:93] op_sel:[1,1] op_sel_hi:[0,1]
	v_pk_fma_f32 v[114:115], v[80:81], v[92:93], v[114:115] op_sel_hi:[1,0,1] neg_lo:[0,0,1]
	v_add_f32_e32 v92, v114, v3
	v_add_f32_e32 v93, v115, v35
	v_pk_mul_f32 v[114:115], v[80:81], v[92:93] op_sel:[1,1] op_sel_hi:[0,1]
	v_pk_fma_f32 v[114:115], v[80:81], v[92:93], v[114:115] op_sel_hi:[1,0,1] neg_lo:[0,0,1]
	v_add_f32_e32 v92, v114, v16
	v_add_f32_e32 v93, v115, v48
	v_pk_mul_f32 v[114:115], v[80:81], v[92:93] op_sel:[1,1] op_sel_hi:[0,1]
	v_pk_fma_f32 v[114:115], v[80:81], v[92:93], v[114:115] op_sel_hi:[1,0,1] neg_lo:[0,0,1]
	v_add_f32_e32 v92, v114, v17
	v_add_f32_e32 v93, v115, v49
	v_pk_mul_f32 v[114:115], v[80:81], v[92:93] op_sel:[1,1] op_sel_hi:[0,1]
	v_pk_fma_f32 v[114:115], v[80:81], v[92:93], v[114:115] op_sel_hi:[1,0,1] neg_lo:[0,0,1]
	v_add_f32_e32 v92, v114, v18
	v_add_f32_e32 v93, v115, v50
	v_pk_mul_f32 v[114:115], v[80:81], v[92:93] op_sel:[1,1] op_sel_hi:[0,1]
	v_pk_fma_f32 v[114:115], v[80:81], v[92:93], v[114:115] op_sel_hi:[1,0,1] neg_lo:[0,0,1]
	v_add_f32_e32 v92, v114, v19
	v_add_f32_e32 v93, v115, v51
	v_pk_mul_f32 v[114:115], v[80:81], v[92:93] op_sel:[1,1] op_sel_hi:[0,1]
	v_pk_fma_f32 v[114:115], v[80:81], v[92:93], v[114:115] op_sel_hi:[1,0,1] neg_lo:[0,0,1]
	v_add_f32_e32 v92, v114, v4
	v_add_f32_e32 v93, v115, v36
	v_pk_mul_f32 v[114:115], v[80:81], v[92:93] op_sel:[1,1] op_sel_hi:[0,1]
	v_pk_fma_f32 v[114:115], v[80:81], v[92:93], v[114:115] op_sel_hi:[1,0,1] neg_lo:[0,0,1]
	v_add_f32_e32 v92, v114, v5
	v_add_f32_e32 v93, v115, v37
	v_pk_mul_f32 v[114:115], v[80:81], v[92:93] op_sel:[1,1] op_sel_hi:[0,1]
	v_pk_fma_f32 v[114:115], v[80:81], v[92:93], v[114:115] op_sel_hi:[1,0,1] neg_lo:[0,0,1]
	v_add_f32_e32 v92, v114, v6
	v_add_f32_e32 v93, v115, v38
	v_pk_mul_f32 v[114:115], v[80:81], v[92:93] op_sel:[1,1] op_sel_hi:[0,1]
	v_pk_fma_f32 v[114:115], v[80:81], v[92:93], v[114:115] op_sel_hi:[1,0,1] neg_lo:[0,0,1]
	v_add_f32_e32 v92, v114, v7
	v_add_f32_e32 v93, v115, v39
	v_pk_mul_f32 v[114:115], v[80:81], v[92:93] op_sel:[1,1] op_sel_hi:[0,1]
	v_pk_fma_f32 v[114:115], v[80:81], v[92:93], v[114:115] op_sel_hi:[1,0,1] neg_lo:[0,0,1]
	v_add_f32_e32 v92, v114, v20
	v_add_f32_e32 v93, v115, v52
	v_pk_mul_f32 v[114:115], v[80:81], v[92:93] op_sel:[1,1] op_sel_hi:[0,1]
	v_pk_fma_f32 v[114:115], v[80:81], v[92:93], v[114:115] op_sel_hi:[1,0,1] neg_lo:[0,0,1]
	v_add_f32_e32 v92, v114, v21
	v_add_f32_e32 v93, v115, v53
	v_pk_mul_f32 v[114:115], v[80:81], v[92:93] op_sel:[1,1] op_sel_hi:[0,1]
; #define LAS __attribute__((address_space(3)))
; template <bool OUT>
; __device__ __forceinline__ void ssm_fast(KArgs ap, int l, LAS unsigned char* lds, const Ctx cx) {
;     ...
;             for (int t = 0; t < 32; ++t) {
;                 const float br = *(const LAS float*)(BU + (t * 128 + p) * 4), bi = *(const LAS float*)(BU + (t * 128 + 64 + p) * 4);
;                 const float nr = are * sr - aim * si + br, ni = are * si + aim * sr + bi; sr = nr; si = ni;
;     ...
;         if (!OUT) { E[(size_t)it * 128 + p] = sr; E[(size_t)it * 128 + 64 + p] = si; }
	v_pk_fma_f32 v[114:115], v[80:81], v[92:93], v[114:115] op_sel_hi:[1,0,1] neg_lo:[0,0,1]
	v_add_f32_e32 v92, v114, v22
	v_add_f32_e32 v93, v115, v54
	v_pk_mul_f32 v[114:115], v[80:81], v[92:93] op_sel:[1,1] op_sel_hi:[0,1]
	v_pk_fma_f32 v[114:115], v[80:81], v[92:93], v[114:115] op_sel_hi:[1,0,1] neg_lo:[0,0,1]
	v_add_f32_e32 v92, v114, v23
	v_add_f32_e32 v93, v115, v55
	v_pk_mul_f32 v[114:115], v[80:81], v[92:93] op_sel:[1,1] op_sel_hi:[0,1]
	v_pk_fma_f32 v[114:115], v[80:81], v[92:93], v[114:115] op_sel_hi:[1,0,1] neg_lo:[0,0,1]
	v_add_f32_e32 v92, v114, v8
	v_add_f32_e32 v93, v115, v40
	v_pk_mul_f32 v[114:115], v[80:81], v[92:93] op_sel:[1,1] op_sel_hi:[0,1]
	v_pk_fma_f32 v[114:115], v[80:81], v[92:93], v[114:115] op_sel_hi:[1,0,1] neg_lo:[0,0,1]
	v_add_f32_e32 v92, v114, v9
	v_add_f32_e32 v93, v115, v41
	v_pk_mul_f32 v[114:115], v[80:81], v[92:93] op_sel:[1,1] op_sel_hi:[0,1]
	v_pk_fma_f32 v[114:115], v[80:81], v[92:93], v[114:115] op_sel_hi:[1,0,1] neg_lo:[0,0,1]
	v_add_f32_e32 v92, v114, v10
	v_add_f32_e32 v93, v115, v42
	v_pk_mul_f32 v[114:115], v[80:81], v[92:93] op_sel:[1,1] op_sel_hi:[0,1]
	v_pk_fma_f32 v[114:115], v[80:81], v[92:93], v[114:115] op_sel_hi:[1,0,1] neg_lo:[0,0,1]
	v_add_f32_e32 v92, v114, v11
	v_add_f32_e32 v93, v115, v43
	v_pk_mul_f32 v[114:115], v[80:81], v[92:93] op_sel:[1,1] op_sel_hi:[0,1]
	v_pk_fma_f32 v[114:115], v[80:81], v[92:93], v[114:115] op_sel_hi:[1,0,1] neg_lo:[0,0,1]
	v_add_f32_e32 v92, v114, v24
	v_add_f32_e32 v93, v115, v56
	v_pk_mul_f32 v[114:115], v[80:81], v[92:93] op_sel:[1,1] op_sel_hi:[0,1]
	v_pk_fma_f32 v[114:115], v[80:81], v[92:93], v[114:115] op_sel_hi:[1,0,1] neg_lo:[0,0,1]
	v_add_f32_e32 v92, v114, v25
	v_add_f32_e32 v93, v115, v57
	v_pk_mul_f32 v[114:115], v[80:81], v[92:93] op_sel:[1,1] op_sel_hi:[0,1]
	v_pk_fma_f32 v[114:115], v[80:81], v[92:93], v[114:115] op_sel_hi:[1,0,1] neg_lo:[0,0,1]
	v_add_f32_e32 v92, v114, v26
	v_add_f32_e32 v93, v115, v58
	v_pk_mul_f32 v[114:115], v[80:81], v[92:93] op_sel:[1,1] op_sel_hi:[0,1]
	v_pk_fma_f32 v[114:115], v[80:81], v[92:93], v[114:115] op_sel_hi:[1,0,1] neg_lo:[0,0,1]
	v_add_f32_e32 v92, v114, v27
	v_add_f32_e32 v93, v115, v59
	v_pk_mul_f32 v[114:115], v[80:81], v[92:93] op_sel:[1,1] op_sel_hi:[0,1]
	v_pk_fma_f32 v[114:115], v[80:81], v[92:93], v[114:115] op_sel_hi:[1,0,1] neg_lo:[0,0,1]
	v_add_f32_e32 v92, v114, v12
	v_add_f32_e32 v93, v115, v44
	v_pk_mul_f32 v[114:115], v[80:81], v[92:93] op_sel:[1,1] op_sel_hi:[0,1]
	v_pk_fma_f32 v[114:115], v[80:81], v[92:93], v[114:115] op_sel_hi:[1,0,1] neg_lo:[0,0,1]
	v_add_f32_e32 v92, v114, v13
	v_add_f32_e32 v93, v115, v45
	v_pk_mul_f32 v[114:115], v[80:81], v[92:93] op_sel:[1,1] op_sel_hi:[0,1]
	v_pk_fma_f32 v[114:115], v[80:81], v[92:93], v[114:115] op_sel_hi:[1,0,1] neg_lo:[0,0,1]
	v_add_f32_e32 v92, v114, v14
	v_add_f32_e32 v93, v115, v46
	v_pk_mul_f32 v[114:115], v[80:81], v[92:93] op_sel:[1,1] op_sel_hi:[0,1]
	v_pk_fma_f32 v[114:115], v[80:81], v[92:93], v[114:115] op_sel_hi:[1,0,1] neg_lo:[0,0,1]
	v_add_f32_e32 v92, v114, v15
	v_add_f32_e32 v93, v115, v47
	v_pk_mul_f32 v[114:115], v[80:81], v[92:93] op_sel:[1,1] op_sel_hi:[0,1]
	v_pk_fma_f32 v[114:115], v[80:81], v[92:93], v[114:115] op_sel_hi:[1,0,1] neg_lo:[0,0,1]
	v_add_f32_e32 v92, v114, v28
	v_add_f32_e32 v93, v115, v60
	v_pk_mul_f32 v[114:115], v[80:81], v[92:93] op_sel:[1,1] op_sel_hi:[0,1]
	v_pk_fma_f32 v[114:115], v[80:81], v[92:93], v[114:115] op_sel_hi:[1,0,1] neg_lo:[0,0,1]
	v_add_f32_e32 v92, v114, v29
	v_add_f32_e32 v93, v115, v61
	v_pk_mul_f32 v[114:115], v[80:81], v[92:93] op_sel:[1,1] op_sel_hi:[0,1]
	v_pk_fma_f32 v[114:115], v[80:81], v[92:93], v[114:115] op_sel_hi:[1,0,1] neg_lo:[0,0,1]
	v_add_f32_e32 v92, v114, v30
	v_add_f32_e32 v93, v115, v62
	v_pk_mul_f32 v[114:115], v[80:81], v[92:93] op_sel:[1,1] op_sel_hi:[0,1]
	v_pk_fma_f32 v[114:115], v[80:81], v[92:93], v[114:115] op_sel_hi:[1,0,1] neg_lo:[0,0,1]
	v_add_f32_e32 v92, v114, v31
	v_add_f32_e32 v93, v115, v63
	s_add_i32 s5, s5, 1
	s_cmp_eq_u32 s5, 4
	s_cbranch_scc0 .LBB0_170
	s_ashr_i32 s5, s4, 31
	s_lshl_b64 s[10:11], s[4:5], 9
	s_add_i32 s4, s4, s8
	v_lshl_add_u64 v[0:1], v[82:83], 0, s[10:11]
	s_cmpk_gt_i32 s4, 0x1fff
	global_store_dword v[0:1], v92, off
	global_store_dword v[0:1], v93, off offset:256
	s_cbranch_scc0 .LBB0_169

; #define LAS __attribute__((address_space(3)))
; __device__ __forceinline__ unsigned f2bf(float f) { unsigned u = __builtin_bit_cast(unsigned, f); return (u + 0x7fffu + ((u >> 16) & 1u)) >> 16; }
; template <bool OUT>
; __device__ __forceinline__ void ssm_fast(KArgs ap, int l, LAS unsigned char* lds, const Ctx cx) {
;     ...
;             for (int t = 0; t < 32; ++t) {
;                 const float br = *(const LAS float*)(BU + (t * 128 + p) * 4), bi = *(const LAS float*)(BU + (t * 128 + 64 + p) * 4);
;                 const float nr = are * sr - aim * si + br, ni = are * si + aim * sr + bi; sr = nr; si = ni;
;                 if (OUT) { asm volatile("" ::: "memory");
;                     *(LAS bf16_t*)(BU + t * 512 + ((((p >> 3)) ^ (t & 15)) << 4) + (p & 7) * 2) = (bf16_t)f2bf(sr);
;                     *(LAS bf16_t*)(BU + t * 512 + (((8 + (p >> 3)) ^ (t & 15)) << 4) + (p & 7) * 2) = (bf16_t)f2bf(si); }
.LBB0_312:
	v_permlane32_swap_b32_e32 v0, v16
	v_permlane32_swap_b32_e32 v1, v17
	v_permlane32_swap_b32_e32 v2, v18
	v_permlane32_swap_b32_e32 v3, v19
	v_permlane32_swap_b32_e32 v4, v20
	v_permlane32_swap_b32_e32 v5, v21
	v_permlane32_swap_b32_e32 v6, v22
	v_permlane32_swap_b32_e32 v7, v23
	v_permlane32_swap_b32_e32 v8, v24
	v_permlane32_swap_b32_e32 v9, v25
	v_permlane32_swap_b32_e32 v10, v26
	v_permlane32_swap_b32_e32 v11, v27
	v_permlane32_swap_b32_e32 v12, v28
	v_permlane32_swap_b32_e32 v13, v29
	v_permlane32_swap_b32_e32 v14, v30
	v_permlane32_swap_b32_e32 v15, v31
	v_permlane32_swap_b32_e32 v32, v48
	v_permlane32_swap_b32_e32 v33, v49
	v_permlane32_swap_b32_e32 v34, v50
	v_permlane32_swap_b32_e32 v35, v51
	v_permlane32_swap_b32_e32 v36, v52
	v_permlane32_swap_b32_e32 v37, v53
	v_permlane32_swap_b32_e32 v38, v54
	v_permlane32_swap_b32_e32 v39, v55
	v_permlane32_swap_b32_e32 v40, v56
	v_permlane32_swap_b32_e32 v41, v57
	v_permlane32_swap_b32_e32 v42, v58
	v_permlane32_swap_b32_e32 v43, v59
	v_permlane32_swap_b32_e32 v44, v60
	v_permlane32_swap_b32_e32 v45, v61
	v_permlane32_swap_b32_e32 v46, v62
	v_permlane32_swap_b32_e32 v47, v63
	v_pk_mul_f32 v[176:177], v[98:99], v[142:143] op_sel:[1,1] op_sel_hi:[0,1]
	v_pk_fma_f32 v[178:179], v[98:99], v[142:143], v[176:177] op_sel_hi:[1,0,1] neg_lo:[0,0,1]
	v_add_f32_e32 v142, v178, v0
	v_add_f32_e32 v143, v179, v32
	v_cvt_pk_bf16_f32 v184, v142, v143
	ds_write_b16 v199, v184 offset:0
	ds_write_b16_d16_hi v207, v184 offset:0
	v_pk_mul_f32 v[176:177], v[98:99], v[142:143] op_sel:[1,1] op_sel_hi:[0,1]
	v_pk_fma_f32 v[178:179], v[98:99], v[142:143], v[176:177] op_sel_hi:[1,0,1] neg_lo:[0,0,1]
	v_add_f32_e32 v142, v178, v1
	v_add_f32_e32 v143, v179, v33
	v_cvt_pk_bf16_f32 v185, v142, v143
	ds_write_b16 v200, v185 offset:512
	ds_write_b16_d16_hi v208, v185 offset:512
	v_pk_mul_f32 v[176:177], v[98:99], v[142:143] op_sel:[1,1] op_sel_hi:[0,1]
	v_pk_fma_f32 v[178:179], v[98:99], v[142:143], v[176:177] op_sel_hi:[1,0,1] neg_lo:[0,0,1]
	v_add_f32_e32 v142, v178, v2
	v_add_f32_e32 v143, v179, v34
	v_cvt_pk_bf16_f32 v186, v142, v143
	ds_write_b16 v201, v186 offset:1024
	ds_write_b16_d16_hi v209, v186 offset:1024
	v_pk_mul_f32 v[176:177], v[98:99], v[142:143] op_sel:[1,1] op_sel_hi:[0,1]
	v_pk_fma_f32 v[178:179], v[98:99], v[142:143], v[176:177] op_sel_hi:[1,0,1] neg_lo:[0,0,1]
	v_add_f32_e32 v142, v178, v3
	v_add_f32_e32 v143, v179, v35
	v_cvt_pk_bf16_f32 v187, v142, v143
	ds_write_b16 v202, v187 offset:1536
	ds_write_b16_d16_hi v210, v187 offset:1536
	v_pk_mul_f32 v[176:177], v[98:99], v[142:143] op_sel:[1,1] op_sel_hi:[0,1]
	v_pk_fma_f32 v[178:179], v[98:99], v[142:143], v[176:177] op_sel_hi:[1,0,1] neg_lo:[0,0,1]
	v_add_f32_e32 v142, v178, v16
	v_add_f32_e32 v143, v179, v48
	v_cvt_pk_bf16_f32 v184, v142, v143
	ds_write_b16 v203, v184 offset:2048
	ds_write_b16_d16_hi v211, v184 offset:2048
	v_pk_mul_f32 v[176:177], v[98:99], v[142:143] op_sel:[1,1] op_sel_hi:[0,1]
	v_pk_fma_f32 v[178:179], v[98:99], v[142:143], v[176:177] op_sel_hi:[1,0,1] neg_lo:[0,0,1]
	v_add_f32_e32 v142, v178, v17
	v_add_f32_e32 v143, v179, v49
	v_cvt_pk_bf16_f32 v185, v142, v143
	ds_write_b16 v204, v185 offset:2560
	ds_write_b16_d16_hi v212, v185 offset:2560
	v_pk_mul_f32 v[176:177], v[98:99], v[142:143] op_sel:[1,1] op_sel_hi:[0,1]
	v_pk_fma_f32 v[178:179], v[98:99], v[142:143], v[176:177] op_sel_hi:[1,0,1] neg_lo:[0,0,1]
	v_add_f32_e32 v142, v178, v18
	v_add_f32_e32 v143, v179, v50
	v_cvt_pk_bf16_f32 v186, v142, v143
	ds_write_b16 v205, v186 offset:3072
	ds_write_b16_d16_hi v213, v186 offset:3072
	v_pk_mul_f32 v[176:177], v[98:99], v[142:143] op_sel:[1,1] op_sel_hi:[0,1]
	v_pk_fma_f32 v[178:179], v[98:99], v[142:143], v[176:177] op_sel_hi:[1,0,1] neg_lo:[0,0,1]
	v_add_f32_e32 v142, v178, v19
	v_add_f32_e32 v143, v179, v51
	v_cvt_pk_bf16_f32 v187, v142, v143
	ds_write_b16 v206, v187 offset:3584
	ds_write_b16_d16_hi v214, v187 offset:3584
	v_pk_mul_f32 v[176:177], v[98:99], v[142:143] op_sel:[1,1] op_sel_hi:[0,1]
	v_pk_fma_f32 v[178:179], v[98:99], v[142:143], v[176:177] op_sel_hi:[1,0,1] neg_lo:[0,0,1]
	v_add_f32_e32 v142, v178, v4
	v_add_f32_e32 v143, v179, v36
	v_cvt_pk_bf16_f32 v184, v142, v143
	ds_write_b16 v207, v184 offset:4096
	ds_write_b16_d16_hi v199, v184 offset:4096
	v_pk_mul_f32 v[176:177], v[98:99], v[142:143] op_sel:[1,1] op_sel_hi:[0,1]
	v_pk_fma_f32 v[178:179], v[98:99], v[142:143], v[176:177] op_sel_hi:[1,0,1] neg_lo:[0,0,1]
	v_add_f32_e32 v142, v178, v5
	v_add_f32_e32 v143, v179, v37
	v_cvt_pk_bf16_f32 v185, v142, v143
	ds_write_b16 v208, v185 offset:4608
	ds_write_b16_d16_hi v200, v185 offset:4608
	v_pk_mul_f32 v[176:177], v[98:99], v[142:143] op_sel:[1,1] op_sel_hi:[0,1]
	v_pk_fma_f32 v[178:179], v[98:99], v[142:143], v[176:177] op_sel_hi:[1,0,1] neg_lo:[0,0,1]
	v_add_f32_e32 v142, v178, v6
	v_add_f32_e32 v143, v179, v38
	v_cvt_pk_bf16_f32 v186, v142, v143
	ds_write_b16 v209, v186 offset:5120
	ds_write_b16_d16_hi v201, v186 offset:5120
	v_pk_mul_f32 v[176:177], v[98:99], v[142:143] op_sel:[1,1] op_sel_hi:[0,1]
	v_pk_fma_f32 v[178:179], v[98:99], v[142:143], v[176:177] op_sel_hi:[1,0,1] neg_lo:[0,0,1]
	v_add_f32_e32 v142, v178, v7
	v_add_f32_e32 v143, v179, v39
	v_cvt_pk_bf16_f32 v187, v142, v143
	ds_write_b16 v210, v187 offset:5632
	ds_write_b16_d16_hi v202, v187 offset:5632
	v_pk_mul_f32 v[176:177], v[98:99], v[142:143] op_sel:[1,1] op_sel_hi:[0,1]
	v_pk_fma_f32 v[178:179], v[98:99], v[142:143], v[176:177] op_sel_hi:[1,0,1] neg_lo:[0,0,1]
	v_add_f32_e32 v142, v178, v20
	v_add_f32_e32 v143, v179, v52
	v_cvt_pk_bf16_f32 v184, v142, v143
	ds_write_b16 v211, v184 offset:6144
	ds_write_b16_d16_hi v203, v184 offset:6144
; #define LAS __attribute__((address_space(3)))
; __device__ __forceinline__ unsigned f2bf(float f) { unsigned u = __builtin_bit_cast(unsigned, f); return (u + 0x7fffu + ((u >> 16) & 1u)) >> 16; }
; template <bool OUT>
; __device__ __forceinline__ void ssm_fast(KArgs ap, int l, LAS unsigned char* lds, const Ctx cx) {
;     ...
;             for (int t = 0; t < 32; ++t) {
;                 const float br = *(const LAS float*)(BU + (t * 128 + p) * 4), bi = *(const LAS float*)(BU + (t * 128 + 64 + p) * 4);
;                 const float nr = are * sr - aim * si + br, ni = are * si + aim * sr + bi; sr = nr; si = ni;
;                 if (OUT) { asm volatile("" ::: "memory");
;                     *(LAS bf16_t*)(BU + t * 512 + ((((p >> 3)) ^ (t & 15)) << 4) + (p & 7) * 2) = (bf16_t)f2bf(sr);
;                     *(LAS bf16_t*)(BU + t * 512 + (((8 + (p >> 3)) ^ (t & 15)) << 4) + (p & 7) * 2) = (bf16_t)f2bf(si); }
	v_pk_mul_f32 v[176:177], v[98:99], v[142:143] op_sel:[1,1] op_sel_hi:[0,1]
	v_pk_fma_f32 v[178:179], v[98:99], v[142:143], v[176:177] op_sel_hi:[1,0,1] neg_lo:[0,0,1]
	v_add_f32_e32 v142, v178, v21
	v_add_f32_e32 v143, v179, v53
	v_cvt_pk_bf16_f32 v185, v142, v143
	ds_write_b16 v212, v185 offset:6656
	ds_write_b16_d16_hi v204, v185 offset:6656
	v_pk_mul_f32 v[176:177], v[98:99], v[142:143] op_sel:[1,1] op_sel_hi:[0,1]
	v_pk_fma_f32 v[178:179], v[98:99], v[142:143], v[176:177] op_sel_hi:[1,0,1] neg_lo:[0,0,1]
	v_add_f32_e32 v142, v178, v22
	v_add_f32_e32 v143, v179, v54
	v_cvt_pk_bf16_f32 v186, v142, v143
	ds_write_b16 v213, v186 offset:7168
	ds_write_b16_d16_hi v205, v186 offset:7168
	v_pk_mul_f32 v[176:177], v[98:99], v[142:143] op_sel:[1,1] op_sel_hi:[0,1]
	v_pk_fma_f32 v[178:179], v[98:99], v[142:143], v[176:177] op_sel_hi:[1,0,1] neg_lo:[0,0,1]
	v_add_f32_e32 v142, v178, v23
	v_add_f32_e32 v143, v179, v55
	v_cvt_pk_bf16_f32 v187, v142, v143
	ds_write_b16 v214, v187 offset:7680
	ds_write_b16_d16_hi v206, v187 offset:7680
	v_pk_mul_f32 v[176:177], v[98:99], v[142:143] op_sel:[1,1] op_sel_hi:[0,1]
	v_pk_fma_f32 v[178:179], v[98:99], v[142:143], v[176:177] op_sel_hi:[1,0,1] neg_lo:[0,0,1]
	v_add_f32_e32 v142, v178, v8
	v_add_f32_e32 v143, v179, v40
	v_cvt_pk_bf16_f32 v184, v142, v143
	ds_write_b16 v199, v184 offset:8192
	ds_write_b16_d16_hi v207, v184 offset:8192
	v_pk_mul_f32 v[176:177], v[98:99], v[142:143] op_sel:[1,1] op_sel_hi:[0,1]
	v_pk_fma_f32 v[178:179], v[98:99], v[142:143], v[176:177] op_sel_hi:[1,0,1] neg_lo:[0,0,1]
	v_add_f32_e32 v142, v178, v9
	v_add_f32_e32 v143, v179, v41
	v_cvt_pk_bf16_f32 v185, v142, v143
	ds_write_b16 v200, v185 offset:8704
	ds_write_b16_d16_hi v208, v185 offset:8704
	v_pk_mul_f32 v[176:177], v[98:99], v[142:143] op_sel:[1,1] op_sel_hi:[0,1]
	v_pk_fma_f32 v[178:179], v[98:99], v[142:143], v[176:177] op_sel_hi:[1,0,1] neg_lo:[0,0,1]
	v_add_f32_e32 v142, v178, v10
	v_add_f32_e32 v143, v179, v42
	v_cvt_pk_bf16_f32 v186, v142, v143
	ds_write_b16 v201, v186 offset:9216
	ds_write_b16_d16_hi v209, v186 offset:9216
	v_pk_mul_f32 v[176:177], v[98:99], v[142:143] op_sel:[1,1] op_sel_hi:[0,1]
	v_pk_fma_f32 v[178:179], v[98:99], v[142:143], v[176:177] op_sel_hi:[1,0,1] neg_lo:[0,0,1]
	v_add_f32_e32 v142, v178, v11
	v_add_f32_e32 v143, v179, v43
	v_cvt_pk_bf16_f32 v187, v142, v143
	ds_write_b16 v202, v187 offset:9728
	ds_write_b16_d16_hi v210, v187 offset:9728
	v_pk_mul_f32 v[176:177], v[98:99], v[142:143] op_sel:[1,1] op_sel_hi:[0,1]
	v_pk_fma_f32 v[178:179], v[98:99], v[142:143], v[176:177] op_sel_hi:[1,0,1] neg_lo:[0,0,1]
	v_add_f32_e32 v142, v178, v24
	v_add_f32_e32 v143, v179, v56
	v_cvt_pk_bf16_f32 v184, v142, v143
	ds_write_b16 v203, v184 offset:10240
	ds_write_b16_d16_hi v211, v184 offset:10240
	v_pk_mul_f32 v[176:177], v[98:99], v[142:143] op_sel:[1,1] op_sel_hi:[0,1]
	v_pk_fma_f32 v[178:179], v[98:99], v[142:143], v[176:177] op_sel_hi:[1,0,1] neg_lo:[0,0,1]
	v_add_f32_e32 v142, v178, v25
	v_add_f32_e32 v143, v179, v57
	v_cvt_pk_bf16_f32 v185, v142, v143
	ds_write_b16 v204, v185 offset:10752
	ds_write_b16_d16_hi v212, v185 offset:10752
	v_pk_mul_f32 v[176:177], v[98:99], v[142:143] op_sel:[1,1] op_sel_hi:[0,1]
	v_pk_fma_f32 v[178:179], v[98:99], v[142:143], v[176:177] op_sel_hi:[1,0,1] neg_lo:[0,0,1]
	v_add_f32_e32 v142, v178, v26
	v_add_f32_e32 v143, v179, v58
	v_cvt_pk_bf16_f32 v186, v142, v143
	ds_write_b16 v205, v186 offset:11264
	ds_write_b16_d16_hi v213, v186 offset:11264
	v_pk_mul_f32 v[176:177], v[98:99], v[142:143] op_sel:[1,1] op_sel_hi:[0,1]
	v_pk_fma_f32 v[178:179], v[98:99], v[142:143], v[176:177] op_sel_hi:[1,0,1] neg_lo:[0,0,1]
	v_add_f32_e32 v142, v178, v27
	v_add_f32_e32 v143, v179, v59
	v_cvt_pk_bf16_f32 v187, v142, v143
	ds_write_b16 v206, v187 offset:11776
	ds_write_b16_d16_hi v214, v187 offset:11776
	v_pk_mul_f32 v[176:177], v[98:99], v[142:143] op_sel:[1,1] op_sel_hi:[0,1]
	v_pk_fma_f32 v[178:179], v[98:99], v[142:143], v[176:177] op_sel_hi:[1,0,1] neg_lo:[0,0,1]
	v_add_f32_e32 v142, v178, v12
	v_add_f32_e32 v143, v179, v44
	v_cvt_pk_bf16_f32 v184, v142, v143
	ds_write_b16 v207, v184 offset:12288
	ds_write_b16_d16_hi v199, v184 offset:12288
	v_pk_mul_f32 v[176:177], v[98:99], v[142:143] op_sel:[1,1] op_sel_hi:[0,1]
	v_pk_fma_f32 v[178:179], v[98:99], v[142:143], v[176:177] op_sel_hi:[1,0,1] neg_lo:[0,0,1]
	v_add_f32_e32 v142, v178, v13
	v_add_f32_e32 v143, v179, v45
	v_cvt_pk_bf16_f32 v185, v142, v143
	ds_write_b16 v208, v185 offset:12800
	ds_write_b16_d16_hi v200, v185 offset:12800
	v_pk_mul_f32 v[176:177], v[98:99], v[142:143] op_sel:[1,1] op_sel_hi:[0,1]
	v_pk_fma_f32 v[178:179], v[98:99], v[142:143], v[176:177] op_sel_hi:[1,0,1] neg_lo:[0,0,1]
	v_add_f32_e32 v142, v178, v14
	v_add_f32_e32 v143, v179, v46
	v_cvt_pk_bf16_f32 v186, v142, v143
	ds_write_b16 v209, v186 offset:13312
	ds_write_b16_d16_hi v201, v186 offset:13312
	v_pk_mul_f32 v[176:177], v[98:99], v[142:143] op_sel:[1,1] op_sel_hi:[0,1]
	v_pk_fma_f32 v[178:179], v[98:99], v[142:143], v[176:177] op_sel_hi:[1,0,1] neg_lo:[0,0,1]
	v_add_f32_e32 v142, v178, v15
	v_add_f32_e32 v143, v179, v47
	v_cvt_pk_bf16_f32 v187, v142, v143
	ds_write_b16 v210, v187 offset:13824
	ds_write_b16_d16_hi v202, v187 offset:13824
	v_pk_mul_f32 v[176:177], v[98:99], v[142:143] op_sel:[1,1] op_sel_hi:[0,1]
	v_pk_fma_f32 v[178:179], v[98:99], v[142:143], v[176:177] op_sel_hi:[1,0,1] neg_lo:[0,0,1]
	v_add_f32_e32 v142, v178, v28
	v_add_f32_e32 v143, v179, v60
	v_cvt_pk_bf16_f32 v184, v142, v143
	ds_write_b16 v211, v184 offset:14336
	ds_write_b16_d16_hi v203, v184 offset:14336
	v_pk_mul_f32 v[176:177], v[98:99], v[142:143] op_sel:[1,1] op_sel_hi:[0,1]
	v_pk_fma_f32 v[178:179], v[98:99], v[142:143], v[176:177] op_sel_hi:[1,0,1] neg_lo:[0,0,1]
	v_add_f32_e32 v142, v178, v29
	v_add_f32_e32 v143, v179, v61
	v_cvt_pk_bf16_f32 v185, v142, v143
	ds_write_b16 v212, v185 offset:14848
	ds_write_b16_d16_hi v204, v185 offset:14848
	v_pk_mul_f32 v[176:177], v[98:99], v[142:143] op_sel:[1,1] op_sel_hi:[0,1]
	v_pk_fma_f32 v[178:179], v[98:99], v[142:143], v[176:177] op_sel_hi:[1,0,1] neg_lo:[0,0,1]
	v_add_f32_e32 v142, v178, v30
	v_add_f32_e32 v143, v179, v62
	v_cvt_pk_bf16_f32 v186, v142, v143
	ds_write_b16 v213, v186 offset:15360
	ds_write_b16_d16_hi v205, v186 offset:15360
	v_pk_mul_f32 v[176:177], v[98:99], v[142:143] op_sel:[1,1] op_sel_hi:[0,1]
	v_pk_fma_f32 v[178:179], v[98:99], v[142:143], v[176:177] op_sel_hi:[1,0,1] neg_lo:[0,0,1]
	v_add_f32_e32 v142, v178, v31
	v_add_f32_e32 v143, v179, v63
	v_cvt_pk_bf16_f32 v187, v142, v143
	ds_write_b16 v214, v187 offset:15872
	ds_write_b16_d16_hi v206, v187 offset:15872
	s_waitcnt lgkmcnt(0)
; #define LAS __attribute__((address_space(3)))
; __device__ __forceinline__ unsigned f2bf(float f) { unsigned u = __builtin_bit_cast(unsigned, f); return (u + 0x7fffu + ((u >> 16) & 1u)) >> 16; }
; #define MFMA16(a_, b_, c_) __builtin_amdgcn_mfma_f32_16x16x32_bf16((a_), (b_), (c_), 0, 0, 0)
; #define WAVE_FENCE() asm volatile("s_waitcnt lgkmcnt(0)" ::: "memory")
; template <bool OUT>
; __device__ __forceinline__ void ssm_fast(KArgs ap, int l, LAS unsigned char* lds, const Ctx cx) {
;     ...
;             if (OUT) {
;                 WAVE_FENCE();
;                 const int row = lane & 15, kq = lane >> 4;
; #pragma unroll
;                 for (int tbk = 0; tbk < 2; ++tbk) { f32x4 acc = (f32x4){0.f, 0.f, 0.f, 0.f};
; #pragma unroll
;                     for (int ks = 0; ks < 4; ++ks) { const bf16x8 af = *(const LAS bf16x8*)(BU + (tbk * 16 + row) * 512 + (((ks * 4 + kq) ^ row) << 4)); acc = MFMA16(af, ct[ks], acc); }
; #pragma unroll
;                     for (int j = 0; j < 4; ++j) { const size_t tok = tk + tbk * 16 + 4 * kq + j;
;                         const float uval = bf2f(uv[tbk][j]);
;                         ypre[tok * 512 + g * 16 + row] = (bf16_t)f2bf(gelu_tanh(acc[j] + dsk * uval)); } }
;             }
	ds_read_b128 v[0:3], v111
	ds_read_b128 v[8:11], v113
	ds_read_b128 v[4:7], v115
	ds_read_b128 v[14:17], v111 offset:8192
	ds_read_b128 v[18:21], v117
	ds_read_b128 v[22:25], v113 offset:8192
	s_waitcnt vmcnt(7)
	v_lshlrev_b32_e32 v28, 16, v144
	v_mov_b32_e32 v13, s9
	v_or_b32_e32 v12, s8, v102
	v_lshlrev_b64 v[12:13], 10, v[12:13]
	v_lshl_add_u64 v[12:13], v[134:135], 0, v[12:13]
	s_waitcnt lgkmcnt(5)
	v_mfma_f32_16x16x32_bf16 v[0:3], v[0:3], v[76:79], 0
	s_waitcnt vmcnt(6)
	v_lshlrev_b32_e32 v29, 16, v131
	v_mov_b32_e32 v27, s9
	v_or_b32_e32 v26, s8, v120
	s_waitcnt lgkmcnt(4)
	v_mfma_f32_16x16x32_bf16 v[0:3], v[8:11], v[84:87], v[0:3]
	ds_read_b128 v[8:11], v115 offset:8192
	s_add_i32 s1, s1, 1
	s_cmp_eq_u32 s1, 4
	s_waitcnt lgkmcnt(4)
	v_mfma_f32_16x16x32_bf16 v[0:3], v[4:7], v[88:91], v[0:3]
	ds_read_b128 v[4:7], v117 offset:8192
	s_waitcnt lgkmcnt(3)
	v_mfma_f32_16x16x32_bf16 v[0:3], v[18:21], v[92:95], v[0:3]
	s_nop 7
	v_fma_f32 v0, v97, v28, v0
	v_mul_f32_e32 v18, 0x3d372713, v0
	v_mul_f32_e32 v18, v0, v18
	v_fma_f32 v18, v0, v18, v0
	v_mul_f32_e32 v18, 0x3f4c422a, v18
	v_add_f32_e32 v18, v18, v18
	v_mul_f32_e32 v18, 0x3fb8aa3b, v18
	v_exp_f32_e32 v18, v18
	v_mul_f32_e32 v0, 0.5, v0
	v_fma_f32 v1, v97, v29, v1
	v_mul_f32_e32 v19, 0x3d372713, v1
	v_add_f32_e32 v18, 1.0, v18
	v_rcp_f32_e32 v18, v18
	v_mul_f32_e32 v19, v1, v19
	v_fma_f32 v19, v1, v19, v1
	v_mul_f32_e32 v19, 0x3f4c422a, v19
	v_fma_f32 v18, v18, -2.0, 1.0
	v_add_f32_e32 v18, 1.0, v18
	v_mul_f32_e32 v0, v0, v18
	v_bfe_u32 v18, v0, 16, 1
	v_add3_u32 v0, v0, v18, s45
	global_store_short_d16_hi v[12:13], v0, off
	s_waitcnt vmcnt(6)
	v_lshlrev_b32_e32 v12, 16, v129
	v_fma_f32 v2, v97, v12, v2
	v_mul_f32_e32 v12, 0x3d372713, v2
	v_mul_f32_e32 v12, v2, v12
	v_fma_f32 v12, v2, v12, v2
	v_mul_f32_e32 v12, 0x3f4c422a, v12
	v_add_f32_e32 v12, v12, v12
	v_mul_f32_e32 v12, 0x3fb8aa3b, v12
	v_exp_f32_e32 v12, v12
	v_add_f32_e32 v19, v19, v19
	v_mul_f32_e32 v19, 0x3fb8aa3b, v19
	v_exp_f32_e32 v19, v19
	v_add_f32_e32 v12, 1.0, v12
	v_rcp_f32_e32 v12, v12
	v_mul_f32_e32 v2, 0.5, v2
	v_add_f32_e32 v19, 1.0, v19
	v_rcp_f32_e32 v19, v19
	v_fma_f32 v12, v12, -2.0, 1.0
	v_add_f32_e32 v12, 1.0, v12
	v_mul_f32_e32 v2, v2, v12
	v_bfe_u32 v12, v2, 16, 1
	v_add3_u32 v2, v2, v12, s45
	s_waitcnt vmcnt(5)
	v_lshlrev_b32_e32 v12, 16, v127
	v_fmac_f32_e32 v3, v97, v12
	v_mul_f32_e32 v12, 0x3d372713, v3
	v_fma_f32 v0, v19, -2.0, 1.0
	v_mul_f32_e32 v12, v3, v12
	v_mul_f32_e32 v1, 0.5, v1
	v_add_f32_e32 v0, 1.0, v0
	v_fma_f32 v12, v3, v12, v3
	v_mul_f32_e32 v0, v1, v0
	v_mul_f32_e32 v12, 0x3f4c422a, v12
	v_bfe_u32 v1, v0, 16, 1
	v_add_f32_e32 v12, v12, v12
	v_add3_u32 v13, v0, v1, s45
	v_lshlrev_b64 v[0:1], 10, v[26:27]
	v_mul_f32_e32 v12, 0x3fb8aa3b, v12
	v_lshl_add_u64 v[0:1], v[134:135], 0, v[0:1]
	v_exp_f32_e32 v18, v12
	global_store_short_d16_hi v[0:1], v13, off
	v_mov_b32_e32 v1, s9
	v_or_b32_e32 v0, s8, v122
	v_mfma_f32_16x16x32_bf16 v[12:15], v[14:17], v[76:79], 0
	v_lshlrev_b64 v[0:1], 10, v[0:1]
	v_lshl_add_u64 v[0:1], v[134:135], 0, v[0:1]
	global_store_short_d16_hi v[0:1], v2, off
	v_add_f32_e32 v0, 1.0, v18
	v_rcp_f32_e32 v0, v0
	s_waitcnt lgkmcnt(2)
	v_mfma_f32_16x16x32_bf16 v[12:15], v[22:25], v[84:87], v[12:15]
	v_mul_f32_e32 v19, 0.5, v3
	v_mov_b32_e32 v17, s9
	v_fma_f32 v18, v0, -2.0, 1.0
	s_waitcnt lgkmcnt(1)
	v_mfma_f32_16x16x32_bf16 v[0:3], v[8:11], v[88:91], v[12:15]
	v_add_f32_e32 v8, 1.0, v18
	v_or_b32_e32 v16, s8, v124
	v_mul_f32_e32 v8, v19, v8
	s_waitcnt lgkmcnt(0)
	v_mfma_f32_16x16x32_bf16 v[0:3], v[4:7], v[92:95], v[0:3]
	s_waitcnt vmcnt(6)
	v_lshlrev_b32_e32 v4, 16, v125
	v_bfe_u32 v9, v8, 16, 1
	v_add3_u32 v7, v8, v9, s45
	s_nop 3
	v_fma_f32 v0, v97, v4, v0
	v_mul_f32_e32 v4, 0x3d372713, v0
	v_mul_f32_e32 v4, v0, v4
	v_fma_f32 v4, v0, v4, v0
	v_mul_f32_e32 v4, 0x3f4c422a, v4
	v_add_f32_e32 v4, v4, v4
	v_mul_f32_e32 v4, 0x3fb8aa3b, v4
	v_exp_f32_e32 v6, v4
	v_lshlrev_b64 v[4:5], 10, v[16:17]
	v_lshl_add_u64 v[4:5], v[134:135], 0, v[4:5]
	global_store_short_d16_hi v[4:5], v7, off
	v_add_f32_e32 v6, 1.0, v6
	v_rcp_f32_e32 v6, v6
	s_waitcnt vmcnt(6)
	v_lshlrev_b32_e32 v7, 16, v123
	v_fma_f32 v7, v97, v7, v1
	v_mul_f32_e32 v1, 0x3d372713, v7
	v_mul_f32_e32 v1, v7, v1
	v_fma_f32 v6, v6, -2.0, 1.0
	v_fma_f32 v1, v7, v1, v7
	v_mul_f32_e32 v0, 0.5, v0
	v_add_f32_e32 v6, 1.0, v6
	v_mul_f32_e32 v1, 0x3f4c422a, v1
	v_mul_f32_e32 v0, v0, v6
	v_add_f32_e32 v1, v1, v1
	v_mov_b32_e32 v5, s9
	v_or_b32_e32 v4, s8, v104
	v_bfe_u32 v6, v0, 16, 1
	v_mul_f32_e32 v1, 0x3fb8aa3b, v1
	v_exp_f32_e32 v8, v1
	v_add3_u32 v6, v0, v6, s45
	v_lshlrev_b64 v[0:1], 10, v[4:5]
	v_lshl_add_u64 v[0:1], v[134:135], 0, v[0:1]
	global_store_short_d16_hi v[0:1], v6, off
	s_waitcnt vmcnt(6)
	v_lshlrev_b32_e32 v6, 16, v121
	v_fma_f32 v2, v97, v6, v2
	v_mul_f32_e32 v6, 0x3d372713, v2
	v_add_f32_e32 v4, 1.0, v8
	v_mul_f32_e32 v6, v2, v6
	v_rcp_f32_e32 v4, v4
	v_fma_f32 v6, v2, v6, v2
	v_mul_f32_e32 v6, 0x3f4c422a, v6
	v_add_f32_e32 v6, v6, v6
	v_mul_f32_e32 v6, 0x3fb8aa3b, v6
	v_fma_f32 v4, v4, -2.0, 1.0
	v_exp_f32_e32 v6, v6
	v_mul_f32_e32 v5, 0.5, v7
	v_add_f32_e32 v4, 1.0, v4
	v_mul_f32_e32 v4, v5, v4
	v_bfe_u32 v5, v4, 16, 1
	v_add3_u32 v4, v4, v5, s45
	v_add_f32_e32 v5, 1.0, v6
	v_rcp_f32_e32 v5, v5
	v_mov_b32_e32 v1, s9
	v_or_b32_e32 v0, s8, v126
	v_lshlrev_b64 v[0:1], 10, v[0:1]
	v_lshl_add_u64 v[0:1], v[134:135], 0, v[0:1]
	global_store_short_d16_hi v[0:1], v4, off
	v_fma_f32 v4, v5, -2.0, 1.0
	s_waitcnt vmcnt(6)
	v_lshlrev_b32_e32 v5, 16, v119
	v_fmac_f32_e32 v3, v97, v5
	v_mul_f32_e32 v5, 0x3d372713, v3
	v_mul_f32_e32 v5, v3, v5
	v_fma_f32 v5, v3, v5, v3
	v_mul_f32_e32 v5, 0x3f4c422a, v5
	v_add_f32_e32 v5, v5, v5
	v_mul_f32_e32 v5, 0x3fb8aa3b, v5
	v_exp_f32_e32 v5, v5
	v_mul_f32_e32 v2, 0.5, v2
	v_add_f32_e32 v4, 1.0, v4
	v_mul_f32_e32 v2, v2, v4
	v_bfe_u32 v4, v2, 16, 1
	v_add3_u32 v2, v2, v4, s45
	v_add_f32_e32 v4, 1.0, v5
	v_rcp_f32_e32 v4, v4
	v_mov_b32_e32 v1, s9
	v_or_b32_e32 v0, s8, v128
	v_lshlrev_b64 v[0:1], 10, v[0:1]
	v_lshl_add_u64 v[0:1], v[134:135], 0, v[0:1]
	global_store_short_d16_hi v[0:1], v2, off
	v_fma_f32 v2, v4, -2.0, 1.0
	v_mul_f32_e32 v3, 0.5, v3
	v_add_f32_e32 v2, 1.0, v2
	v_mov_b32_e32 v1, s9
	v_or_b32_e32 v0, s8, v130
	v_mul_f32_e32 v2, v3, v2
	v_bfe_u32 v3, v2, 16, 1
	v_lshlrev_b64 v[0:1], 10, v[0:1]
	v_add3_u32 v2, v2, v3, s45
	v_lshl_add_u64 v[0:1], v[134:135], 0, v[0:1]
	global_store_short_d16_hi v[0:1], v2, off
	s_cbranch_scc0 .LBB0_311
	s_add_i32 s0, s0, s7
	s_cmpk_gt_i32 s0, 0x1fff
	s_cbranch_scc0 .LBB0_310
